# one (not two) P.V MFMA after the step barrier; the other one sits between the two P stores
# speedup vs baseline: 1.0016x; 1.0011x over previous
; #define DMAWAIT() asm volatile("s_waitcnt vmcnt(0)" ::: "memory")
; #define SMX_FIN(pbuf) do { _Pragma("unroll") for (int r = 0; r < 16; ++r) l_reg += S[r]; \
;     PK4S(0, po0); PK4S(8, po1); \
;     *(bf16x8*)(pw + (pbuf) * 16384) = po0; *(bf16x8*)(pw + (pbuf) * 16384 + 16) = po1; } while (0)
; #define VRD(D0, X) do { X##0 = tr_read<v_rd_off(D0, 0, 0)>(vb); X##1 = tr_read<v_rd_off(D0, 0, 1)>(vb); X##2 = tr_read<v_rd_off(D0, 1, 0)>(vb); X##3 = tr_read<v_rd_off(D0, 1, 1)>(vb); \
;     X##4 = tr_read<v_rd_off(D0, 2, 0)>(vb); X##5 = tr_read<v_rd_off(D0, 2, 1)>(vb); X##6 = tr_read<v_rd_off(D0, 3, 0)>(vb); X##7 = tr_read<v_rd_off(D0, 3, 1)>(vb); } while (0)
; #define LWAIT() do { asm volatile("s_waitcnt lgkmcnt(0)" ::: "memory"); SBAR(); } while (0)
; #define VMMP(D0, X) do { if (!(PROBE & 8)) VMM(D0, X); } while (0)
; #define SMXP(c) do { if (!(PROBE & 2)) { if (more) SMX_CH(c); } } while (0)
; template <int PROBE, int MODE>
; DI void dattn_body(const u16* __restrict__ Qb, const u16* __restrict__ Kh, const u16* __restrict__ Vh, u16* __restrict__ Ob, const u16* __restrict__ O1, float lam, const float* __restrict__ subg, int seq, int q0, float kmax2, char* lds) {
;     ...
;     LWAIT(); VRD(1, vc); VMMP(0, va); SMXP(0);
;     LWAIT(); VRD(2, va); VMMP(1, vc); SMXP(1);
;     LWAIT(); VRD(3, vc); VMMP(2, va); SMXP(2);
;     LWAIT(); VMMP(3, vc); SMXP(3);
;     if (!(PROBE & 2)) { if (more) SMX_FIN((j + 1) & 1); }
;     DMAWAIT();
;     __syncthreads();
.Lfast0_k_done:
	s_waitcnt lgkmcnt(6)
	v_mfma_f32_32x32x16_bf16 v[0:15], v[114:117], v[234:237], v[0:15]
	ds_read_b64_tr_b16 v[138:139], v216 offset:0x200
	ds_read_b64_tr_b16 v[140:141], v216 offset:0xa00
	s_waitcnt lgkmcnt(6)
	v_mfma_f32_32x32x16_bf16 v[0:15], v[130:133], v[238:241], v[0:15]
	ds_read_b64_tr_b16 v[142:143], v216 offset:0x1200
	ds_read_b64_tr_b16 v[144:145], v216 offset:0x1a00
	s_nop 1
	v_fma_f32 v118, v64, s12, v160
	v_fma_f32 v119, v65, s12, v160
	v_fma_f32 v120, v66, s12, v160
	v_fma_f32 v121, v67, s12, v160
	s_waitcnt lgkmcnt(6)
	v_mfma_f32_32x32x16_bf16 v[0:15], v[162:165], v[242:245], v[0:15]
	ds_read_b64_tr_b16 v[134:135], v233 offset:0x2200
	ds_read_b64_tr_b16 v[136:137], v233 offset:0x2a00
	v_fma_f32 v122, v68, s12, v160
	v_fma_f32 v123, v69, s12, v160
	v_exp_f32_e32 v118, v118
	v_exp_f32_e32 v119, v119
	s_waitcnt lgkmcnt(6)
	v_mfma_f32_32x32x16_bf16 v[0:15], v[166:169], v[246:249], v[0:15]
	ds_read_b64_tr_b16 v[126:127], v233 offset:0x3200
	ds_read_b64_tr_b16 v[128:129], v233 offset:0x3a00
	v_fma_f32 v124, v70, s12, v160
	v_fma_f32 v125, v71, s12, v160
	v_exp_f32_e32 v120, v120
	v_exp_f32_e32 v121, v121
	s_waitcnt lgkmcnt(6)
	v_mfma_f32_32x32x16_bf16 v[16:31], v[114:117], v[138:141], v[16:31]
	ds_read_b64_tr_b16 v[146:147], v216 offset:0x400
	ds_read_b64_tr_b16 v[148:149], v216 offset:0xc00
	v_exp_f32_e32 v122, v122
	v_exp_f32_e32 v123, v123
	v_add_f32_e32 v209, v118, v209
	v_add_f32_e32 v209, v119, v209
	s_waitcnt lgkmcnt(6)
	v_mfma_f32_32x32x16_bf16 v[16:31], v[130:133], v[142:145], v[16:31]
	ds_read_b64_tr_b16 v[142:143], v216 offset:0x1400
	ds_read_b64_tr_b16 v[144:145], v216 offset:0x1c00
	v_exp_f32_e32 v124, v124
	v_exp_f32_e32 v125, v125
	v_add_f32_e32 v209, v120, v209
	v_add_f32_e32 v209, v121, v209
	v_fma_f32 v244, v72, s12, v160
	v_fma_f32 v245, v73, s12, v160
	s_waitcnt lgkmcnt(6)
	v_mfma_f32_32x32x16_bf16 v[16:31], v[162:165], v[134:137], v[16:31]
	ds_read_b64_tr_b16 v[138:139], v233 offset:0x2400
	ds_read_b64_tr_b16 v[140:141], v233 offset:0x2c00
	v_fma_f32 v246, v74, s12, v160
	v_fma_f32 v247, v75, s12, v160
	v_add_f32_e32 v209, v122, v209
	v_add_f32_e32 v209, v123, v209
	s_waitcnt lgkmcnt(6)
	v_mfma_f32_32x32x16_bf16 v[16:31], v[166:169], v[126:129], v[16:31]
	ds_read_b64_tr_b16 v[64:65], v233 offset:0x3400
	ds_read_b64_tr_b16 v[66:67], v233 offset:0x3c00
	v_fma_f32 v76, v76, s12, v160
	v_fma_f32 v77, v77, s12, v160
	v_fma_f32 v78, v78, s12, v160
	v_fma_f32 v79, v79, s12, v160
	s_waitcnt lgkmcnt(6)
	v_mfma_f32_32x32x16_bf16 v[32:47], v[114:117], v[146:149], v[32:47]
	v_exp_f32_e32 v244, v244
	v_exp_f32_e32 v245, v245
	v_add_f32_e32 v209, v124, v209
	v_add_f32_e32 v209, v125, v209
	s_waitcnt lgkmcnt(4)
	v_mfma_f32_32x32x16_bf16 v[32:47], v[130:133], v[142:145], v[32:47]
	ds_read_b64_tr_b16 v[142:143], v216 offset:0x600
	ds_read_b64_tr_b16 v[144:145], v216 offset:0xe00
	ds_read_b64_tr_b16 v[126:127], v216 offset:0x1600
	ds_read_b64_tr_b16 v[128:129], v216 offset:0x1e00
	v_exp_f32_e32 v246, v246
	v_exp_f32_e32 v247, v247
	s_waitcnt lgkmcnt(6)
	v_mfma_f32_32x32x16_bf16 v[32:47], v[162:165], v[138:141], v[32:47]
	ds_read_b64_tr_b16 v[134:135], v233 offset:0x2600
	ds_read_b64_tr_b16 v[136:137], v233 offset:0x2e00
	v_exp_f32_e32 v76, v76
	v_exp_f32_e32 v77, v77
	v_add_f32_e32 v209, v244, v209
	v_add_f32_e32 v209, v245, v209
	s_waitcnt lgkmcnt(6)
	v_mfma_f32_32x32x16_bf16 v[32:47], v[166:169], v[64:67], v[32:47]
	ds_read_b64_tr_b16 v[68:69], v233 offset:0x3600
	ds_read_b64_tr_b16 v[70:71], v233 offset:0x3e00
	v_exp_f32_e32 v78, v78
	v_exp_f32_e32 v79, v79
	v_add_f32_e32 v209, v246, v209
	v_add_f32_e32 v209, v247, v209
	s_waitcnt lgkmcnt(6)
	v_mfma_f32_32x32x16_bf16 v[48:63], v[114:117], v[142:145], v[48:63]
	v_add_u32_e32 v64, s19, v211
	v_add_f32_e32 v209, v76, v209
	v_add_f32_e32 v209, v77, v209
	v_cvt_pk_bf16_f32 v114, v118, v119
	v_cvt_pk_bf16_f32 v115, v120, v121
	v_cvt_pk_bf16_f32 v116, v122, v123
	v_cvt_pk_bf16_f32 v117, v124, v125
	s_waitcnt lgkmcnt(4)
	v_mfma_f32_32x32x16_bf16 v[48:63], v[130:133], v[126:129], v[48:63]
	v_add_f32_e32 v209, v78, v209
	v_add_f32_e32 v209, v79, v209
	v_permlane32_swap_b32_e32 v114, v116
	v_permlane32_swap_b32_e32 v115, v117
	v_cvt_pk_bf16_f32 v130, v244, v245
	v_cvt_pk_bf16_f32 v131, v246, v247
	v_cvt_pk_bf16_f32 v132, v76, v77
	v_cvt_pk_bf16_f32 v133, v78, v79
	ds_write_b128 v64, v[114:117]
	s_waitcnt lgkmcnt(3)
	v_mfma_f32_32x32x16_bf16 v[48:63], v[162:165], v[134:137], v[48:63]
	v_permlane32_swap_b32_e32 v130, v132
	v_permlane32_swap_b32_e32 v131, v133
	ds_write_b128 v64, v[130:133] offset:16
	s_add_i32 s55, s55, 1
	s_add_i32 s18, s18, 64
	s_add_i32 s54, s54, 0x8000
	s_add_i32 s100, s18, -1
	s_cmp_ge_i32 s100, s33
	s_cselect_b32 s100, 1, 0
	s_sub_i32 s101, s18, 64
	s_cmp_le_i32 s101, s35
	s_cselect_b32 s101, 1, 0
	s_and_b32 s100, s100, s101
	s_cmp_eq_u32 s83, s55
	s_waitcnt vmcnt(0) lgkmcnt(0)
	s_barrier
	v_mfma_f32_32x32x16_bf16 v[48:63], v[166:169], v[68:71], v[48:63]
	s_cbranch_scc1 .LBB0_265
	s_cmp_lg_u32 s100, 0
	s_cbranch_scc1 .Lgen0
	s_branch .Lfast0

; #define DMAWAIT() asm volatile("s_waitcnt vmcnt(0)" ::: "memory")
; #define SMX_FIN(pbuf) do { _Pragma("unroll") for (int r = 0; r < 16; ++r) l_reg += S[r]; \
;     PK4S(0, po0); PK4S(8, po1); \
;     *(bf16x8*)(pw + (pbuf) * 16384) = po0; *(bf16x8*)(pw + (pbuf) * 16384 + 16) = po1; } while (0)
; #define VRD(D0, X) do { X##0 = tr_read<v_rd_off(D0, 0, 0)>(vb); X##1 = tr_read<v_rd_off(D0, 0, 1)>(vb); X##2 = tr_read<v_rd_off(D0, 1, 0)>(vb); X##3 = tr_read<v_rd_off(D0, 1, 1)>(vb); \
;     X##4 = tr_read<v_rd_off(D0, 2, 0)>(vb); X##5 = tr_read<v_rd_off(D0, 2, 1)>(vb); X##6 = tr_read<v_rd_off(D0, 3, 0)>(vb); X##7 = tr_read<v_rd_off(D0, 3, 1)>(vb); } while (0)
; #define LWAIT() do { asm volatile("s_waitcnt lgkmcnt(0)" ::: "memory"); SBAR(); } while (0)
; #define VMMP(D0, X) do { if (!(PROBE & 8)) VMM(D0, X); } while (0)
; #define SMXP(c) do { if (!(PROBE & 2)) { if (more) SMX_CH(c); } } while (0)
; template <int PROBE, int MODE>
; DI void dattn_body(const u16* __restrict__ Qb, const u16* __restrict__ Kh, const u16* __restrict__ Vh, u16* __restrict__ Ob, const u16* __restrict__ O1, float lam, const float* __restrict__ subg, int seq, int q0, float kmax2, char* lds) {
;     ...
;     LWAIT(); VRD(1, vc); VMMP(0, va); SMXP(0);
;     LWAIT(); VRD(2, va); VMMP(1, vc); SMXP(1);
;     LWAIT(); VRD(3, vc); VMMP(2, va); SMXP(2);
;     LWAIT(); VMMP(3, vc); SMXP(3);
;     if (!(PROBE & 2)) { if (more) SMX_FIN((j + 1) & 1); }
;     DMAWAIT();
;     __syncthreads();
.Lfast1_k_done:
	s_waitcnt lgkmcnt(6)
	v_mfma_f32_32x32x16_bf16 v[0:15], v[114:117], v[234:237], v[0:15]
	ds_read_b64_tr_b16 v[138:139], v215 offset:0x200
	ds_read_b64_tr_b16 v[140:141], v215 offset:0xa00
	s_waitcnt lgkmcnt(6)
	v_mfma_f32_32x32x16_bf16 v[0:15], v[130:133], v[238:241], v[0:15]
	ds_read_b64_tr_b16 v[142:143], v215 offset:0x1200
	ds_read_b64_tr_b16 v[144:145], v215 offset:0x1a00
	s_nop 1
	v_fma_f32 v118, v64, s12, v160
	v_fma_f32 v119, v65, s12, v160
	v_fma_f32 v120, v66, s12, v160
	v_fma_f32 v121, v67, s12, v160
	s_waitcnt lgkmcnt(6)
	v_mfma_f32_32x32x16_bf16 v[0:15], v[162:165], v[242:245], v[0:15]
	ds_read_b64_tr_b16 v[134:135], v233 offset:0x2200
	ds_read_b64_tr_b16 v[136:137], v233 offset:0x2a00
	v_fma_f32 v122, v68, s12, v160
	v_fma_f32 v123, v69, s12, v160
	v_exp_f32_e32 v118, v118
	v_exp_f32_e32 v119, v119
	s_waitcnt lgkmcnt(6)
	v_mfma_f32_32x32x16_bf16 v[0:15], v[166:169], v[246:249], v[0:15]
	ds_read_b64_tr_b16 v[126:127], v233 offset:0x3200
	ds_read_b64_tr_b16 v[128:129], v233 offset:0x3a00
	v_fma_f32 v124, v70, s12, v160
	v_fma_f32 v125, v71, s12, v160
	v_exp_f32_e32 v120, v120
	v_exp_f32_e32 v121, v121
	s_waitcnt lgkmcnt(6)
	v_mfma_f32_32x32x16_bf16 v[16:31], v[114:117], v[138:141], v[16:31]
	ds_read_b64_tr_b16 v[146:147], v215 offset:0x400
	ds_read_b64_tr_b16 v[148:149], v215 offset:0xc00
	v_exp_f32_e32 v122, v122
	v_exp_f32_e32 v123, v123
	v_add_f32_e32 v208, v118, v208
	v_add_f32_e32 v208, v119, v208
	s_waitcnt lgkmcnt(6)
	v_mfma_f32_32x32x16_bf16 v[16:31], v[130:133], v[142:145], v[16:31]
	ds_read_b64_tr_b16 v[142:143], v215 offset:0x1400
	ds_read_b64_tr_b16 v[144:145], v215 offset:0x1c00
	v_exp_f32_e32 v124, v124
	v_exp_f32_e32 v125, v125
	v_add_f32_e32 v208, v120, v208
	v_add_f32_e32 v208, v121, v208
	v_fma_f32 v244, v72, s12, v160
	v_fma_f32 v245, v73, s12, v160
	s_waitcnt lgkmcnt(6)
	v_mfma_f32_32x32x16_bf16 v[16:31], v[162:165], v[134:137], v[16:31]
	ds_read_b64_tr_b16 v[138:139], v233 offset:0x2400
	ds_read_b64_tr_b16 v[140:141], v233 offset:0x2c00
	v_fma_f32 v246, v74, s12, v160
	v_fma_f32 v247, v75, s12, v160
	v_add_f32_e32 v208, v122, v208
	v_add_f32_e32 v208, v123, v208
	s_waitcnt lgkmcnt(6)
	v_mfma_f32_32x32x16_bf16 v[16:31], v[166:169], v[126:129], v[16:31]
	ds_read_b64_tr_b16 v[64:65], v233 offset:0x3400
	ds_read_b64_tr_b16 v[66:67], v233 offset:0x3c00
	v_fma_f32 v76, v76, s12, v160
	v_fma_f32 v77, v77, s12, v160
	v_fma_f32 v78, v78, s12, v160
	v_fma_f32 v79, v79, s12, v160
	s_waitcnt lgkmcnt(6)
	v_mfma_f32_32x32x16_bf16 v[32:47], v[114:117], v[146:149], v[32:47]
	v_exp_f32_e32 v244, v244
	v_exp_f32_e32 v245, v245
	v_add_f32_e32 v208, v124, v208
	v_add_f32_e32 v208, v125, v208
	s_waitcnt lgkmcnt(4)
	v_mfma_f32_32x32x16_bf16 v[32:47], v[130:133], v[142:145], v[32:47]
	ds_read_b64_tr_b16 v[142:143], v215 offset:0x600
	ds_read_b64_tr_b16 v[144:145], v215 offset:0xe00
	ds_read_b64_tr_b16 v[126:127], v215 offset:0x1600
	ds_read_b64_tr_b16 v[128:129], v215 offset:0x1e00
	v_exp_f32_e32 v246, v246
	v_exp_f32_e32 v247, v247
	s_waitcnt lgkmcnt(6)
	v_mfma_f32_32x32x16_bf16 v[32:47], v[162:165], v[138:141], v[32:47]
	ds_read_b64_tr_b16 v[134:135], v233 offset:0x2600
	ds_read_b64_tr_b16 v[136:137], v233 offset:0x2e00
	v_exp_f32_e32 v76, v76
	v_exp_f32_e32 v77, v77
	v_add_f32_e32 v208, v244, v208
	v_add_f32_e32 v208, v245, v208
	s_waitcnt lgkmcnt(6)
	v_mfma_f32_32x32x16_bf16 v[32:47], v[166:169], v[64:67], v[32:47]
	ds_read_b64_tr_b16 v[68:69], v233 offset:0x3600
	ds_read_b64_tr_b16 v[70:71], v233 offset:0x3e00
	v_exp_f32_e32 v78, v78
	v_exp_f32_e32 v79, v79
	v_add_f32_e32 v208, v246, v208
	v_add_f32_e32 v208, v247, v208
	s_waitcnt lgkmcnt(6)
	v_mfma_f32_32x32x16_bf16 v[48:63], v[114:117], v[142:145], v[48:63]
	v_add_u32_e32 v64, s1, v210
	v_add_f32_e32 v208, v76, v208
	v_add_f32_e32 v208, v77, v208
	v_cvt_pk_bf16_f32 v114, v118, v119
	v_cvt_pk_bf16_f32 v115, v120, v121
	v_cvt_pk_bf16_f32 v116, v122, v123
	v_cvt_pk_bf16_f32 v117, v124, v125
	s_waitcnt lgkmcnt(4)
	v_mfma_f32_32x32x16_bf16 v[48:63], v[130:133], v[126:129], v[48:63]
	v_add_f32_e32 v208, v78, v208
	v_add_f32_e32 v208, v79, v208
	v_permlane32_swap_b32_e32 v114, v116
	v_permlane32_swap_b32_e32 v115, v117
	v_cvt_pk_bf16_f32 v130, v244, v245
	v_cvt_pk_bf16_f32 v131, v246, v247
	v_cvt_pk_bf16_f32 v132, v76, v77
	v_cvt_pk_bf16_f32 v133, v78, v79
	ds_write_b128 v64, v[114:117]
	s_waitcnt lgkmcnt(3)
	v_mfma_f32_32x32x16_bf16 v[48:63], v[162:165], v[134:137], v[48:63]
	v_permlane32_swap_b32_e32 v130, v132
	v_permlane32_swap_b32_e32 v131, v133
	ds_write_b128 v64, v[130:133] offset:16
	s_add_i32 s40, s40, 1
	s_add_i32 s0, s0, 64
	s_add_i32 s25, s25, 0x8000
	s_add_i32 s100, s0, -1
	s_cmp_ge_i32 s100, s33
	s_cselect_b32 s100, 1, 0
	s_sub_i32 s101, s0, 64
	s_cmp_le_i32 s101, s35
	s_cselect_b32 s101, 1, 0
	s_and_b32 s100, s100, s101
	s_cmp_eq_u32 s83, s40
	s_waitcnt vmcnt(0) lgkmcnt(0)
	s_barrier
	v_mfma_f32_32x32x16_bf16 v[48:63], v[166:169], v[68:71], v[48:63]
	s_cbranch_scc1 .LBB0_303
	s_cmp_lg_u32 s100, 0
	s_cbranch_scc1 .Lgen1
	s_branch .Lfast1
